# scan loader: decay/a lora epilogues use both lane halves via v_permlane32_swap (8 values per lane instead of 16 on half the lanes), branchless decay select
# baseline (speedup 1.0000x reference)
; #define LAS __attribute__((address_space(3)))
; DI float tanh_fast(float x) { return 1.f - 2.f * __builtin_amdgcn_rcpf(1.f + __expf(2.f * x)); }
; DI void unpack8(const u32x4 w, float* f) { f[0] = bflo(w.x); f[1] = bfhi(w.x); f[2] = bflo(w.y); f[3] = bfhi(w.y); f[4] = bflo(w.z); f[5] = bfhi(w.z); f[6] = bflo(w.w); f[7] = bfhi(w.w); }
; DI u32x4 pack8(const float* f) { u32x4 w; w.x = pk2(f[0], f[1]); w.y = pk2(f[2], f[3]); w.z = pk2(f[4], f[5]); w.w = pk2(f[6], f[7]); return w; }
; DI void scan_bh2(const Args& a, int l, int bh, int halfsel, LAS unsigned char* lds) {
;     ...
;         for (int cc = 0; cc <= SEQ / T; ++cc) {
;             if (cc < SEQ / T) {
;                 const int tg = cc * T + lw * 8 + token;
;                 const u32x4 rw0 = nxt[0], rw1 = nxt[1], ra0 = nxt[2], ra1 = nxt[3], rr0 = nxt[4], rr1 = nxt[5], rk0 = nxt[6], rk1 = nxt[7], rv0 = nxt[8], rv1 = nxt[9];
;                 bf16x8 bwq[2][4];
; #pragma unroll
;                 for (int ks = 0; ks < 2; ++ks)
; #pragma unroll
;                     for (int n = 0; n < 4; ++n) bwq[ks][n] = *(const bf16x8*)(W + W_WL + (size_t)(h * 64 + n * 16 + fr) * 64 + ks * 32 + fq * 8);
;                 float cf[8], pf[8], t8[8];
;                 unpack8(rw0, cf); unpack8(rw1, pf);
; #pragma unroll
;                 for (int i = 0; i < 8; ++i) t8[i] = tanh_fast(cf[i] + (pf[i] - cf[i]) * muw[i]);
;                 *(LAS u32x4*)(A_w + token * 72 + c8) = pack8(t8);
;                 unpack8(ra0, cf); unpack8(ra1, pf);
; #pragma unroll
;                 for (int i = 0; i < 8; ++i) t8[i] = cf[i] + (pf[i] - cf[i]) * mua[i];
;                 *(LAS u32x4*)(A_a + token * 72 + c8) = pack8(t8);
;                 asm volatile("s_waitcnt lgkmcnt(0)" ::: "memory");
; #pragma unroll
;                 for (int which = 0; which < 2; ++which) {
;                     f32x4 acc[4];
; #pragma unroll
;                     for (int n = 0; n < 4; ++n) acc[n] = (f32x4){0.f, 0.f, 0.f, 0.f};
;                     const LAS bf16_t* As = which ? A_a : A_w;
; #pragma unroll
;                     for (int ks = 0; ks < 2; ++ks) {
;                         const bf16x8 af = *(const LAS bf16x8*)(As + fr * 72 + ks * 32 + fq * 8);
; #pragma unroll
;                         for (int n = 0; n < 4; ++n) acc[n] = MFMA16(af, bwq[ks][n], acc[n]);
;                     }
.LBB0_421:
	s_cmpk_eq_i32 s6, 0x80
	s_cbranch_scc1 .LBB0_420
	s_waitcnt vmcnt(4)
	v_lshlrev_b32_e32 v128, 16, v56
	v_lshlrev_b32_e32 v130, 16, v60
	v_sub_f32_e32 v130, v130, v128
	v_fmac_f32_e32 v128, v40, v130
	v_add_f32_e32 v128, v128, v128
	v_mul_f32_e32 v128, 0x3fb8aa3b, v128
	v_exp_f32_e32 v128, v128
	v_and_b32_e32 v131, 0xffff0000, v60
	v_lshlrev_b32_e32 v132, 16, v61
	v_and_b32_e32 v133, 0xffff0000, v61
	v_add_f32_e32 v128, 1.0, v128
	v_rcp_f32_e32 v130, v128
	v_and_b32_e32 v128, 0xffff0000, v56
	v_sub_f32_e32 v131, v131, v128
	v_fmac_f32_e32 v128, v41, v131
	v_add_f32_e32 v128, v128, v128
	v_mul_f32_e32 v128, 0x3fb8aa3b, v128
	v_exp_f32_e32 v128, v128
	global_load_dwordx4 v[112:115], v[152:153], off
	global_load_dwordx4 v[116:119], v[152:153], off offset:2048
	global_load_dwordx4 v[120:123], v[168:169], off
	global_load_dwordx4 v[124:127], v[170:171], off
	global_load_dwordx4 v[96:99], v[152:153], off offset:64
	global_load_dwordx4 v[100:103], v[152:153], off offset:2112
	global_load_dwordx4 v[104:107], v[172:173], off
	global_load_dwordx4 v[108:111], v[174:175], off
	v_lshlrev_b32_e32 v134, 16, v62
	v_and_b32_e32 v135, 0xffff0000, v62
	v_add_f32_e32 v128, 1.0, v128
	v_rcp_f32_e32 v131, v128
	v_lshlrev_b32_e32 v128, 16, v57
	v_sub_f32_e32 v132, v132, v128
	v_fmac_f32_e32 v128, v42, v132
	v_add_f32_e32 v128, v128, v128
	v_mul_f32_e32 v128, 0x3fb8aa3b, v128
	v_exp_f32_e32 v128, v128
	v_lshlrev_b32_e32 v136, 16, v63
	v_and_b32_e32 v137, 0xffff0000, v63
	v_pk_fma_f32 v[130:131], v[130:131], 2.0, 1.0 op_sel_hi:[1,0,0] neg_lo:[1,0,0] neg_hi:[1,0,0]
	v_add_f32_e32 v128, 1.0, v128
	v_rcp_f32_e32 v132, v128
	v_and_b32_e32 v128, 0xffff0000, v57
	v_sub_f32_e32 v133, v133, v128
	v_fmac_f32_e32 v128, v43, v133
	v_add_f32_e32 v128, v128, v128
	v_mul_f32_e32 v128, 0x3fb8aa3b, v128
	v_exp_f32_e32 v128, v128
	v_cvt_pk_bf16_f32 v130, v130, v131
	s_waitcnt vmcnt(11)
	v_lshlrev_b32_e32 v138, 16, v71
	v_and_b32_e32 v139, 0xffff0000, v71
	v_add_f32_e32 v128, 1.0, v128
	v_rcp_f32_e32 v133, v128
	v_lshlrev_b32_e32 v128, 16, v58
	v_sub_f32_e32 v134, v134, v128
	v_fmac_f32_e32 v128, v36, v134
	v_add_f32_e32 v128, v128, v128
	v_mul_f32_e32 v128, 0x3fb8aa3b, v128
	v_exp_f32_e32 v128, v128
	v_pk_fma_f32 v[132:133], v[132:133], 2.0, 1.0 op_sel_hi:[1,0,0] neg_lo:[1,0,0] neg_hi:[1,0,0]
	v_add_f32_e32 v128, 1.0, v128
	v_rcp_f32_e32 v134, v128
	v_and_b32_e32 v128, 0xffff0000, v58
	v_sub_f32_e32 v135, v135, v128
	v_fmac_f32_e32 v128, v37, v135
	v_add_f32_e32 v128, v128, v128
	v_mul_f32_e32 v128, 0x3fb8aa3b, v128
	v_exp_f32_e32 v128, v128
	v_cvt_pk_bf16_f32 v131, v132, v133
	v_add_f32_e32 v128, 1.0, v128
	v_rcp_f32_e32 v135, v128
	v_lshlrev_b32_e32 v128, 16, v59
	v_sub_f32_e32 v136, v136, v128
	v_fmac_f32_e32 v128, v38, v136
	v_add_f32_e32 v128, v128, v128
	v_mul_f32_e32 v128, 0x3fb8aa3b, v128
	v_exp_f32_e32 v128, v128
	v_pk_fma_f32 v[134:135], v[134:135], 2.0, 1.0 op_sel_hi:[1,0,0] neg_lo:[1,0,0] neg_hi:[1,0,0]
	v_add_f32_e32 v128, 1.0, v128
	v_rcp_f32_e32 v136, v128
	v_and_b32_e32 v128, 0xffff0000, v59
	v_sub_f32_e32 v137, v137, v128
	v_fmac_f32_e32 v128, v39, v137
	v_add_f32_e32 v128, v128, v128
	v_mul_f32_e32 v128, 0x3fb8aa3b, v128
	v_exp_f32_e32 v128, v128
	v_cvt_pk_bf16_f32 v132, v134, v135
	v_lshlrev_b32_e32 v134, 16, v69
	v_and_b32_e32 v135, 0xffff0000, v69
	v_add_f32_e32 v128, 1.0, v128
	v_rcp_f32_e32 v137, v128
	s_nop 0
	v_pk_fma_f32 v[136:137], v[136:137], 2.0, 1.0 op_sel_hi:[1,0,0] neg_lo:[1,0,0] neg_hi:[1,0,0]
	s_nop 0
	v_cvt_pk_bf16_f32 v133, v136, v137
	ds_write_b128 v204, v[130:133]
	v_lshlrev_b32_e32 v130, 16, v64
	v_and_b32_e32 v131, 0xffff0000, v64
	v_lshlrev_b32_e32 v132, 16, v68
	v_and_b32_e32 v133, 0xffff0000, v68
	v_pk_add_f32 v[132:133], v[132:133], v[130:131] neg_lo:[0,1] neg_hi:[0,1]
	v_lshlrev_b32_e32 v136, 16, v70
	v_pk_fma_f32 v[130:131], v[44:45], v[132:133], v[130:131]
	v_lshlrev_b32_e32 v132, 16, v65
	v_and_b32_e32 v133, 0xffff0000, v65
	v_pk_add_f32 v[134:135], v[134:135], v[132:133] neg_lo:[0,1] neg_hi:[0,1]
	v_and_b32_e32 v137, 0xffff0000, v70
	v_pk_fma_f32 v[132:133], v[46:47], v[134:135], v[132:133]
	v_lshlrev_b32_e32 v134, 16, v66
	v_and_b32_e32 v135, 0xffff0000, v66
	v_pk_add_f32 v[136:137], v[136:137], v[134:135] neg_lo:[0,1] neg_hi:[0,1]
	v_cvt_pk_bf16_f32 v130, v130, v131
	v_pk_fma_f32 v[134:135], v[52:53], v[136:137], v[134:135]
	v_lshlrev_b32_e32 v136, 16, v67
	v_and_b32_e32 v137, 0xffff0000, v67
	v_pk_add_f32 v[138:139], v[138:139], v[136:137] neg_lo:[0,1] neg_hi:[0,1]
	v_cvt_pk_bf16_f32 v131, v132, v133
	v_pk_fma_f32 v[136:137], v[54:55], v[138:139], v[136:137]
	v_cvt_pk_bf16_f32 v132, v134, v135
	v_cvt_pk_bf16_f32 v133, v136, v137
	ds_write_b128 v204, v[130:133] offset:2304
	s_waitcnt lgkmcnt(0)
	ds_read_b128 v[130:133], v208
	s_waitcnt vmcnt(7) lgkmcnt(0)
	v_mfma_f32_16x16x32_bf16 v[112:115], v[130:133], v[112:115], 0
	s_waitcnt vmcnt(6)
	v_mfma_f32_16x16x32_bf16 v[116:119], v[130:133], v[116:119], 0
	s_waitcnt vmcnt(5)
	v_mfma_f32_16x16x32_bf16 v[120:123], v[130:133], v[120:123], 0
	s_waitcnt vmcnt(4)
	v_mfma_f32_16x16x32_bf16 v[124:127], v[130:133], v[124:127], 0
	ds_read_b128 v[130:133], v208 offset:64
	s_waitcnt vmcnt(3) lgkmcnt(0)
	v_mfma_f32_16x16x32_bf16 v[142:145], v[130:133], v[96:99], v[112:115]
	s_waitcnt vmcnt(2)
	v_mfma_f32_16x16x32_bf16 v[138:141], v[130:133], v[100:103], v[116:119]
	s_waitcnt vmcnt(1)
	v_mfma_f32_16x16x32_bf16 v[134:137], v[130:133], v[104:107], v[120:123]
	s_waitcnt vmcnt(0)
; #define LAS __attribute__((address_space(3)))
; DI bf16_t tobf(float x) { return (bf16_t)(pk2(x, 0.f) & 0xffffu); }
; DI float sigm(float x) { return __builtin_amdgcn_rcpf(1.f + __expf(-x)); }
; DI void scan_bh2(const Args& a, int l, int bh, int halfsel, LAS unsigned char* lds) {
;     ...
;                     if (which == 0) {
; #pragma unroll
;                         for (int ks = 0; ks < 2; ++ks)
; #pragma unroll
;                             for (int n = 0; n < 4; ++n) bwq[ks][n] = *(const bf16x8*)(W + W_AL + (size_t)(h * 64 + n * 16 + fr) * 64 + ks * 32 + fq * 8);
;                     }
;                     if (fq < 2) {
;                         LAS bf16_t* dst = which ? a_s : omd_s;
; #pragma unroll
;                         for (int n = 0; n < 4; ++n)
; #pragma unroll
;                             for (int r = 0; r < 4; ++r) {
;                                 float res;
;                                 if (which) res = sigm(a0c[n] + acc[n][r]);
;                                 else { const float x = -(w0c[n] + acc[n][r]); const float ew = 0.60653065971f * __builtin_amdgcn_rcpf(1.f + __expf(x));
;                                        res = ew > 0.03f ? 1.f - __expf(-ew) : ew * (1.f - ew * (0.5f - ew * (1.f / 6.f))); }
;                                 dst[(fq * 4 + r) * 64 + n * 16 + fr] = tobf(res);
;                             }
	v_mfma_f32_16x16x32_bf16 v[130:133], v[130:133], v[108:111], v[124:127]
	global_load_dwordx4 v[112:115], v[176:177], off
	global_load_dwordx4 v[116:119], v[176:177], off offset:2048
	global_load_dwordx4 v[120:123], v[178:179], off
	global_load_dwordx4 v[124:127], v[180:181], off
	global_load_dwordx4 v[96:99], v[176:177], off offset:64
	global_load_dwordx4 v[100:103], v[176:177], off offset:2112
	global_load_dwordx4 v[104:107], v[182:183], off
	global_load_dwordx4 v[108:111], v[184:185], off
	s_nop 3
	v_permlane32_swap_b32_e32 v142, v134
	v_permlane32_swap_b32_e32 v143, v135
	v_permlane32_swap_b32_e32 v144, v136
	v_permlane32_swap_b32_e32 v145, v137
	v_permlane32_swap_b32_e32 v138, v130
	v_permlane32_swap_b32_e32 v139, v131
	v_permlane32_swap_b32_e32 v140, v132
	v_permlane32_swap_b32_e32 v141, v133
	v_cndmask_b32_e64 v251, v198, v196, s[38:39]
	v_cndmask_b32_e64 v252, v199, v197, s[38:39]
	v_mov_b32_e32 v253, 0xfffffc40
	v_cndmask_b32_e64 v253, v253, 0, s[38:39]
	v_add_u32_e32 v253, v206, v253
	s_mov_b32 s4, 0x3cf5c28f
	s_mov_b32 s7, 0xbe2aaaab
	v_add_f32_e32 v142, v251, v142
	v_add_f32_e32 v143, v251, v143
	v_add_f32_e32 v144, v251, v144
	v_add_f32_e32 v145, v251, v145
	v_mul_f32_e32 v142, 0xbfb8aa3b, v142
	v_mul_f32_e32 v143, 0xbfb8aa3b, v143
	v_mul_f32_e32 v144, 0xbfb8aa3b, v144
	v_mul_f32_e32 v145, 0xbfb8aa3b, v145
	v_exp_f32_e32 v142, v142
	v_exp_f32_e32 v143, v143
	v_exp_f32_e32 v144, v144
	v_exp_f32_e32 v145, v145
	v_add_f32_e32 v142, 1.0, v142
	v_add_f32_e32 v143, 1.0, v143
	v_add_f32_e32 v144, 1.0, v144
	v_add_f32_e32 v145, 1.0, v145
	v_rcp_f32_e32 v142, v142
	v_rcp_f32_e32 v143, v143
	v_rcp_f32_e32 v144, v144
	v_rcp_f32_e32 v145, v145
	v_mul_f32_e32 v142, 0x3f1b4598, v142
	v_mul_f32_e32 v143, 0x3f1b4598, v143
	v_mul_f32_e32 v144, 0x3f1b4598, v144
	v_mul_f32_e32 v145, 0x3f1b4598, v145
	v_mul_f32_e32 v133, 0xbfb8aa3b, v142
	v_mul_f32_e32 v134, 0xbfb8aa3b, v143
	v_mul_f32_e32 v135, 0xbfb8aa3b, v144
	v_mul_f32_e32 v136, 0xbfb8aa3b, v145
	v_exp_f32_e32 v133, v133
	v_exp_f32_e32 v134, v134
	v_exp_f32_e32 v135, v135
	v_exp_f32_e32 v136, v136
	v_fma_f32 v128, v142, s7, 0.5
	v_fma_f32 v130, v143, s7, 0.5
	v_fma_f32 v131, v144, s7, 0.5
	v_fma_f32 v132, v145, s7, 0.5
	v_fma_f32 v128, -v142, v128, 1.0
	v_fma_f32 v130, -v143, v130, 1.0
	v_fma_f32 v131, -v144, v131, 1.0
	v_fma_f32 v132, -v145, v132, 1.0
	v_mul_f32_e32 v128, v142, v128
	v_mul_f32_e32 v130, v143, v130
	v_mul_f32_e32 v131, v144, v131
	v_mul_f32_e32 v132, v145, v132
	v_sub_f32_e32 v133, 1.0, v133
	v_sub_f32_e32 v134, 1.0, v134
	v_sub_f32_e32 v135, 1.0, v135
	v_sub_f32_e32 v136, 1.0, v136
	v_cmp_nlt_f32_e32 vcc, s4, v142
	v_cndmask_b32_e32 v128, v133, v128, vcc
	v_cmp_nlt_f32_e32 vcc, s4, v143
	v_cndmask_b32_e32 v130, v134, v130, vcc
	v_cmp_nlt_f32_e32 vcc, s4, v144
	v_cndmask_b32_e32 v131, v135, v131, vcc
	v_cmp_nlt_f32_e32 vcc, s4, v145
	v_cndmask_b32_e32 v132, v136, v132, vcc
	v_cvt_pk_bf16_f32 v128, v128, v130
	v_cvt_pk_bf16_f32 v131, v131, v132
	ds_write_b16 v253, v128 offset:5632
	ds_write_b16_d16_hi v253, v128 offset:5760
	ds_write_b16 v253, v131 offset:5888
	ds_write_b16_d16_hi v253, v131 offset:6016
	v_add_f32_e32 v138, v252, v138
	v_add_f32_e32 v139, v252, v139
	v_add_f32_e32 v140, v252, v140
	v_add_f32_e32 v141, v252, v141
	v_mul_f32_e32 v138, 0xbfb8aa3b, v138
	v_mul_f32_e32 v139, 0xbfb8aa3b, v139
	v_mul_f32_e32 v140, 0xbfb8aa3b, v140
	v_mul_f32_e32 v141, 0xbfb8aa3b, v141
	v_exp_f32_e32 v138, v138
	v_exp_f32_e32 v139, v139
	v_exp_f32_e32 v140, v140
	v_exp_f32_e32 v141, v141
	v_add_f32_e32 v138, 1.0, v138
	v_add_f32_e32 v139, 1.0, v139
	v_add_f32_e32 v140, 1.0, v140
	v_add_f32_e32 v141, 1.0, v141
	v_rcp_f32_e32 v138, v138
	v_rcp_f32_e32 v139, v139
	v_rcp_f32_e32 v140, v140
	v_rcp_f32_e32 v141, v141
	v_mul_f32_e32 v138, 0x3f1b4598, v138
	v_mul_f32_e32 v139, 0x3f1b4598, v139
	v_mul_f32_e32 v140, 0x3f1b4598, v140
	v_mul_f32_e32 v141, 0x3f1b4598, v141
	v_mul_f32_e32 v133, 0xbfb8aa3b, v138
	v_mul_f32_e32 v134, 0xbfb8aa3b, v139
	v_mul_f32_e32 v135, 0xbfb8aa3b, v140
	v_mul_f32_e32 v136, 0xbfb8aa3b, v141
	v_exp_f32_e32 v133, v133
	v_exp_f32_e32 v134, v134
	v_exp_f32_e32 v135, v135
	v_exp_f32_e32 v136, v136
	v_fma_f32 v128, v138, s7, 0.5
	v_fma_f32 v130, v139, s7, 0.5
	v_fma_f32 v131, v140, s7, 0.5
	v_fma_f32 v132, v141, s7, 0.5
	v_fma_f32 v128, -v138, v128, 1.0
	v_fma_f32 v130, -v139, v130, 1.0
	v_fma_f32 v131, -v140, v131, 1.0
	v_fma_f32 v132, -v141, v132, 1.0
	v_mul_f32_e32 v128, v138, v128
	v_mul_f32_e32 v130, v139, v130
	v_mul_f32_e32 v131, v140, v131
	v_mul_f32_e32 v132, v141, v132
	v_sub_f32_e32 v133, 1.0, v133
	v_sub_f32_e32 v134, 1.0, v134
	v_sub_f32_e32 v135, 1.0, v135
	v_sub_f32_e32 v136, 1.0, v136
	v_cmp_nlt_f32_e32 vcc, s4, v138
	v_cndmask_b32_e32 v128, v133, v128, vcc
	v_cmp_nlt_f32_e32 vcc, s4, v139
	v_cndmask_b32_e32 v130, v134, v130, vcc
	v_cmp_nlt_f32_e32 vcc, s4, v140
	v_cndmask_b32_e32 v131, v135, v131, vcc
	v_cmp_nlt_f32_e32 vcc, s4, v141
	v_cndmask_b32_e32 v132, v136, v132, vcc
	v_cvt_pk_bf16_f32 v128, v128, v130
	v_cvt_pk_bf16_f32 v131, v131, v132
	ds_write_b16 v253, v128 offset:5664
	ds_write_b16_d16_hi v253, v128 offset:5792
	ds_write_b16 v253, v131 offset:5920
	ds_write_b16_d16_hi v253, v131 offset:6048
	ds_read_b128 v[130:133], v208 offset:2304
	s_waitcnt vmcnt(7) lgkmcnt(0)
	v_mfma_f32_16x16x32_bf16 v[112:115], v[130:133], v[112:115], 0
	s_waitcnt vmcnt(6)
	v_mfma_f32_16x16x32_bf16 v[134:137], v[130:133], v[116:119], 0
	s_waitcnt vmcnt(5)
	v_mfma_f32_16x16x32_bf16 v[120:123], v[130:133], v[120:123], 0
	s_waitcnt vmcnt(4)
	v_mfma_f32_16x16x32_bf16 v[124:127], v[130:133], v[124:127], 0
	ds_read_b128 v[130:133], v208 offset:2368
	s_waitcnt vmcnt(3) lgkmcnt(0)
; #define LAS __attribute__((address_space(3)))
; DI bf16_t tobf(float x) { return (bf16_t)(pk2(x, 0.f) & 0xffffu); }
; DI float sigm(float x) { return __builtin_amdgcn_rcpf(1.f + __expf(-x)); }
; DI void unpack8(const u32x4 w, float* f) { f[0] = bflo(w.x); f[1] = bfhi(w.x); f[2] = bflo(w.y); f[3] = bfhi(w.y); f[4] = bflo(w.z); f[5] = bfhi(w.z); f[6] = bflo(w.w); f[7] = bfhi(w.w); }
; DI void scan_bh2(const Args& a, int l, int bh, int halfsel, LAS unsigned char* lds) {
;     ...
;                     if (which == 0) {
; #pragma unroll
;                         for (int ks = 0; ks < 2; ++ks)
; #pragma unroll
;                             for (int n = 0; n < 4; ++n) bwq[ks][n] = *(const bf16x8*)(W + W_AL + (size_t)(h * 64 + n * 16 + fr) * 64 + ks * 32 + fq * 8);
;                     }
;                     if (fq < 2) {
;                         LAS bf16_t* dst = which ? a_s : omd_s;
; #pragma unroll
;                         for (int n = 0; n < 4; ++n)
; #pragma unroll
;                             for (int r = 0; r < 4; ++r) {
;                                 float res;
;                                 if (which) res = sigm(a0c[n] + acc[n][r]);
;                                 else { const float x = -(w0c[n] + acc[n][r]); const float ew = 0.60653065971f * __builtin_amdgcn_rcpf(1.f + __expf(x));
;                                        res = ew > 0.03f ? 1.f - __expf(-ew) : ew * (1.f - ew * (0.5f - ew * (1.f / 6.f))); }
;                                 dst[(fq * 4 + r) * 64 + n * 16 + fr] = tobf(res);
;                             }
;                     }
;                 }
;                 asm volatile("s_waitcnt lgkmcnt(0)" ::: "memory");
;                 float r[8], k[8], v[8], av[8], od[8];
;                 unpack8(rr0, cf); unpack8(rr1, pf);
; #pragma unroll
;                 for (int i = 0; i < 8; ++i) r[i] = cf[i] + (pf[i] - cf[i]) * mur[i];
;                 unpack8(rk0, cf); unpack8(rk1, pf);
; #pragma unroll
;                 for (int i = 0; i < 8; ++i) k[i] = cf[i] + (pf[i] - cf[i]) * muk[i];
;                 unpack8(rv0, cf); unpack8(rv1, pf);
; #pragma unroll
;                 for (int i = 0; i < 8; ++i) v[i] = cf[i] + (pf[i] - cf[i]) * muv[i];
;                 unpack8(*(const LAS u32x4*)(a_s + token * 64 + c8), av); unpack8(*(const LAS u32x4*)(omd_s + token * 64 + c8), od);
	v_mfma_f32_16x16x32_bf16 v[116:119], v[130:133], v[96:99], v[112:115]
	s_waitcnt vmcnt(2)
	v_mfma_f32_16x16x32_bf16 v[112:115], v[130:133], v[100:103], v[134:137]
	s_waitcnt vmcnt(1)
	v_mfma_f32_16x16x32_bf16 v[100:103], v[130:133], v[104:107], v[120:123]
	s_waitcnt vmcnt(0)
	v_mfma_f32_16x16x32_bf16 v[96:99], v[130:133], v[108:111], v[124:127]
	v_cndmask_b32_e64 v251, v202, v200, s[38:39]
	v_cndmask_b32_e64 v252, v203, v201, s[38:39]
	s_nop 7
	v_permlane32_swap_b32_e32 v116, v100
	v_permlane32_swap_b32_e32 v117, v101
	v_permlane32_swap_b32_e32 v118, v102
	v_permlane32_swap_b32_e32 v119, v103
	v_permlane32_swap_b32_e32 v112, v96
	v_permlane32_swap_b32_e32 v113, v97
	v_permlane32_swap_b32_e32 v114, v98
	v_permlane32_swap_b32_e32 v115, v99
	v_add_f32_e32 v116, v251, v116
	v_add_f32_e32 v117, v251, v117
	v_add_f32_e32 v118, v251, v118
	v_add_f32_e32 v119, v251, v119
	v_add_f32_e32 v112, v252, v112
	v_add_f32_e32 v113, v252, v113
	v_add_f32_e32 v114, v252, v114
	v_add_f32_e32 v115, v252, v115
	v_mul_f32_e32 v116, 0xbfb8aa3b, v116
	v_mul_f32_e32 v117, 0xbfb8aa3b, v117
	v_mul_f32_e32 v118, 0xbfb8aa3b, v118
	v_mul_f32_e32 v119, 0xbfb8aa3b, v119
	v_mul_f32_e32 v112, 0xbfb8aa3b, v112
	v_mul_f32_e32 v113, 0xbfb8aa3b, v113
	v_mul_f32_e32 v114, 0xbfb8aa3b, v114
	v_mul_f32_e32 v115, 0xbfb8aa3b, v115
	v_exp_f32_e32 v116, v116
	v_exp_f32_e32 v117, v117
	v_exp_f32_e32 v118, v118
	v_exp_f32_e32 v119, v119
	v_exp_f32_e32 v112, v112
	v_exp_f32_e32 v113, v113
	v_exp_f32_e32 v114, v114
	v_exp_f32_e32 v115, v115
	v_add_f32_e32 v116, 1.0, v116
	v_add_f32_e32 v117, 1.0, v117
	v_add_f32_e32 v118, 1.0, v118
	v_add_f32_e32 v119, 1.0, v119
	v_add_f32_e32 v112, 1.0, v112
	v_add_f32_e32 v113, 1.0, v113
	v_add_f32_e32 v114, 1.0, v114
	v_add_f32_e32 v115, 1.0, v115
	v_rcp_f32_e32 v116, v116
	v_rcp_f32_e32 v117, v117
	v_rcp_f32_e32 v118, v118
	v_rcp_f32_e32 v119, v119
	v_rcp_f32_e32 v112, v112
	v_rcp_f32_e32 v113, v113
	v_rcp_f32_e32 v114, v114
	v_rcp_f32_e32 v115, v115
	v_cvt_pk_bf16_f32 v116, v116, v117
	v_cvt_pk_bf16_f32 v118, v118, v119
	v_cvt_pk_bf16_f32 v112, v112, v113
	v_cvt_pk_bf16_f32 v114, v114, v115
	ds_write_b16 v253, v116 offset:4608
	ds_write_b16_d16_hi v253, v116 offset:4736
	ds_write_b16 v253, v118 offset:4864
	ds_write_b16_d16_hi v253, v118 offset:4992
	ds_write_b16 v253, v112 offset:4640
	ds_write_b16_d16_hi v253, v112 offset:4768
	ds_write_b16 v253, v114 offset:4896
	ds_write_b16_d16_hi v253, v114 offset:5024
	s_nop 4
	v_lshlrev_b32_e32 v96, 16, v76
	v_and_b32_e32 v97, 0xffff0000, v76
	v_lshlrev_b32_e32 v98, 16, v72
	v_and_b32_e32 v99, 0xffff0000, v72
	v_pk_add_f32 v[98:99], v[98:99], v[96:97] neg_lo:[0,1] neg_hi:[0,1]
	s_waitcnt lgkmcnt(0)
	v_lshlrev_b32_e32 v116, 16, v82
	v_pk_fma_f32 v[104:105], v[4:5], v[98:99], v[96:97]
	v_lshlrev_b32_e32 v96, 16, v77
	v_and_b32_e32 v97, 0xffff0000, v77
	v_lshlrev_b32_e32 v98, 16, v73
	v_and_b32_e32 v99, 0xffff0000, v73
	v_pk_add_f32 v[98:99], v[98:99], v[96:97] neg_lo:[0,1] neg_hi:[0,1]
	v_and_b32_e32 v117, 0xffff0000, v82
	v_pk_fma_f32 v[106:107], v[6:7], v[98:99], v[96:97]
	v_lshlrev_b32_e32 v96, 16, v78
	v_and_b32_e32 v97, 0xffff0000, v78
	v_lshlrev_b32_e32 v98, 16, v74
	v_and_b32_e32 v99, 0xffff0000, v74
	v_pk_add_f32 v[98:99], v[98:99], v[96:97] neg_lo:[0,1] neg_hi:[0,1]
	v_lshlrev_b32_e32 v118, 16, v86
	v_pk_fma_f32 v[110:111], v[0:1], v[98:99], v[96:97]
	v_lshlrev_b32_e32 v96, 16, v79
	v_and_b32_e32 v97, 0xffff0000, v79
	v_lshlrev_b32_e32 v98, 16, v75
	v_and_b32_e32 v99, 0xffff0000, v75
	v_pk_add_f32 v[98:99], v[98:99], v[96:97] neg_lo:[0,1] neg_hi:[0,1]
	v_and_b32_e32 v119, 0xffff0000, v86
	v_pk_fma_f32 v[132:133], v[2:3], v[98:99], v[96:97]
	v_lshlrev_b32_e32 v96, 16, v88
	v_and_b32_e32 v97, 0xffff0000, v88
	v_lshlrev_b32_e32 v98, 16, v92
	v_and_b32_e32 v99, 0xffff0000, v92
	v_pk_add_f32 v[98:99], v[98:99], v[96:97] neg_lo:[0,1] neg_hi:[0,1]
	v_pk_add_f32 v[118:119], v[118:119], v[116:117] neg_lo:[0,1] neg_hi:[0,1]
	v_pk_fma_f32 v[134:135], v[48:49], v[98:99], v[96:97]
	v_lshlrev_b32_e32 v96, 16, v89
	v_and_b32_e32 v97, 0xffff0000, v89
	v_lshlrev_b32_e32 v98, 16, v93
	v_and_b32_e32 v99, 0xffff0000, v93
	v_pk_add_f32 v[98:99], v[98:99], v[96:97] neg_lo:[0,1] neg_hi:[0,1]
	v_pk_fma_f32 v[120:121], v[8:9], v[118:119], v[116:117]
	v_pk_fma_f32 v[136:137], v[50:51], v[98:99], v[96:97]
	v_lshlrev_b32_e32 v96, 16, v90
	v_and_b32_e32 v97, 0xffff0000, v90
	v_lshlrev_b32_e32 v98, 16, v94
	v_and_b32_e32 v99, 0xffff0000, v94
	v_pk_add_f32 v[98:99], v[98:99], v[96:97] neg_lo:[0,1] neg_hi:[0,1]
	v_pk_mul_f32 v[118:119], v[16:17], v[120:121]
	v_pk_fma_f32 v[138:139], v[32:33], v[98:99], v[96:97]
	v_lshlrev_b32_e32 v96, 16, v91
	v_and_b32_e32 v97, 0xffff0000, v91
	v_lshlrev_b32_e32 v98, 16, v95
	v_and_b32_e32 v99, 0xffff0000, v95
	v_pk_add_f32 v[98:99], v[98:99], v[96:97] neg_lo:[0,1] neg_hi:[0,1]
	v_lshlrev_b32_e32 v108, 16, v83
	v_pk_fma_f32 v[140:141], v[34:35], v[98:99], v[96:97]
	ds_read_b128 v[96:99], v207 offset:4608
	ds_read_b128 v[100:103], v207 offset:5632
	v_and_b32_e32 v109, 0xffff0000, v83
	v_lshlrev_b32_e32 v112, 16, v87
	v_and_b32_e32 v113, 0xffff0000, v87
	s_waitcnt lgkmcnt(1)
; #define LAS __attribute__((address_space(3)))
; DI void unpack8(const u32x4 w, float* f) { f[0] = bflo(w.x); f[1] = bfhi(w.x); f[2] = bflo(w.y); f[3] = bfhi(w.y); f[4] = bflo(w.z); f[5] = bfhi(w.z); f[6] = bflo(w.w); f[7] = bfhi(w.w); }
; DI u32x4 pack8(const float* f) { u32x4 w; w.x = pk2(f[0], f[1]); w.y = pk2(f[2], f[3]); w.z = pk2(f[4], f[5]); w.w = pk2(f[6], f[7]); return w; }
; DI float red8(float x) { x = red4(x); x = dpp_add<0x141>(x); return x; }
; DI void scan_bh2(const Args& a, int l, int bh, int halfsel, LAS unsigned char* lds) {
;     ...
;                 unpack8(*(const LAS u32x4*)(a_s + token * 64 + c8), av); unpack8(*(const LAS u32x4*)(omd_s + token * 64 + c8), od);
;                 float kk[8], bb[8], kp[8]; float ss = 0.f;
; #pragma unroll
;                 for (int i = 0; i < 8; ++i) { kk[i] = k[i] * kkp[i]; ss += kk[i] * kk[i]; }
;                 ss = red8(ss);
;                 const float rn = rsqrtf(fmaxf(ss, 1e-24f));
; #pragma unroll
;                 for (int i = 0; i < 8; ++i) { kk[i] *= rn; bb[i] = kk[i] * av[i]; kp[i] = k[i] * (1.f + (av[i] - 1.f) * kap[i]); }
;                 const u32x4 r16 = pack8(r), kp16 = pack8(kp), kk16 = pack8(kk), bb16 = pack8(bb), v16 = pack8(v);
;                 if (halfsel == 0) { bf16_t* op = PREP3 + ((size_t)bh * SEQ + tg) * 192 + c8; *(u32x4*)op = r16; *(u32x4*)(op + 64) = kp16; *(u32x4*)(op + 128) = v16; }
	v_lshlrev_b32_e32 v116, 16, v98
	v_and_b32_e32 v117, 0xffff0000, v98
	v_pk_add_f32 v[122:123], v[116:117], -1.0 op_sel_hi:[1,0]
	v_pk_add_f32 v[112:113], v[112:113], v[108:109] neg_lo:[0,1] neg_hi:[0,1]
	v_pk_fma_f32 v[122:123], v[24:25], v[122:123], 1.0 op_sel_hi:[1,1,0]
	v_pk_fma_f32 v[108:109], v[10:11], v[112:113], v[108:109]
	v_pk_mul_f32 v[142:143], v[120:121], v[122:123]
	v_lshlrev_b32_e32 v120, 16, v81
	v_and_b32_e32 v121, 0xffff0000, v81
	v_lshlrev_b32_e32 v122, 16, v85
	v_and_b32_e32 v123, 0xffff0000, v85
	v_pk_add_f32 v[122:123], v[122:123], v[120:121] neg_lo:[0,1] neg_hi:[0,1]
	v_lshlrev_b32_e32 v112, 16, v99
	v_pk_fma_f32 v[124:125], v[14:15], v[122:123], v[120:121]
	v_lshlrev_b32_e32 v120, 16, v97
	v_and_b32_e32 v121, 0xffff0000, v97
	v_pk_add_f32 v[126:127], v[120:121], -1.0 op_sel_hi:[1,0]
	v_pk_mul_f32 v[122:123], v[22:23], v[124:125]
	v_pk_fma_f32 v[126:127], v[30:31], v[126:127], 1.0 op_sel_hi:[1,1,0]
	v_pk_mul_f32 v[144:145], v[122:123], v[122:123]
	v_pk_mul_f32 v[212:213], v[124:125], v[126:127]
	v_lshlrev_b32_e32 v124, 16, v80
	v_and_b32_e32 v125, 0xffff0000, v80
	v_lshlrev_b32_e32 v126, 16, v84
	v_and_b32_e32 v127, 0xffff0000, v84
	v_pk_add_f32 v[126:127], v[126:127], v[124:125] neg_lo:[0,1] neg_hi:[0,1]
	v_and_b32_e32 v113, 0xffff0000, v99
	v_pk_fma_f32 v[214:215], v[12:13], v[126:127], v[124:125]
	v_lshlrev_b32_e32 v124, 16, v96
	v_pk_mul_f32 v[126:127], v[20:21], v[214:215]
	v_and_b32_e32 v125, 0xffff0000, v96
	v_pk_mul_f32 v[96:97], v[126:127], v[126:127]
	v_pk_mul_f32 v[98:99], v[118:119], v[118:119]
	v_add_f32_e32 v96, v96, v97
	v_add_f32_e32 v96, v144, v96
	v_add_f32_e32 v96, v145, v96
	v_pk_mul_f32 v[114:115], v[18:19], v[108:109]
	v_add_f32_e32 v96, v98, v96
	v_pk_mul_f32 v[130:131], v[114:115], v[114:115]
	v_add_f32_e32 v96, v99, v96
	v_add_f32_e32 v96, v130, v96
	v_add_f32_e32 v96, v131, v96
	v_pk_add_f32 v[216:217], v[124:125], -1.0 op_sel_hi:[1,0]
	v_readlane_b32 s0, v248, 24
	v_add_f32_dpp v96, v96, v96 quad_perm:[1,0,3,2] row_mask:0xf bank_mask:0xf bound_ctrl:1
	v_pk_fma_f32 v[216:217], v[28:29], v[216:217], 1.0 op_sel_hi:[1,1,0]
	v_readlane_b32 s1, v248, 25
	v_add_f32_dpp v130, v96, v96 quad_perm:[2,3,0,1] row_mask:0xf bank_mask:0xf bound_ctrl:1
	v_pk_add_f32 v[96:97], v[112:113], -1.0 op_sel_hi:[1,0]
	v_pk_mul_f32 v[214:215], v[214:215], v[216:217]
	v_pk_fma_f32 v[96:97], v[26:27], v[96:97], 1.0 op_sel_hi:[1,1,0]
	v_mov_b32_dpp v131, v130 row_half_mirror row_mask:0xf bank_mask:0xf bound_ctrl:1
	v_pk_mul_f32 v[96:97], v[108:109], v[96:97]
	v_cvt_pk_bf16_f32 v108, v104, v105
	v_cvt_pk_bf16_f32 v109, v106, v107
	v_cvt_pk_bf16_f32 v110, v110, v111
	v_cvt_pk_bf16_f32 v111, v132, v133
	v_cvt_pk_bf16_f32 v104, v214, v215
	v_cvt_pk_bf16_f32 v105, v212, v213
	v_cvt_pk_bf16_f32 v106, v142, v143
	v_cvt_pk_bf16_f32 v107, v96, v97
	v_cvt_pk_bf16_f32 v96, v134, v135
	v_cvt_pk_bf16_f32 v97, v136, v137
	v_cvt_pk_bf16_f32 v98, v138, v139
	s_andn2_b64 vcc, exec, s[0:1]
	v_cvt_pk_bf16_f32 v99, v140, v141
	s_cbranch_vccnz .LBB0_492
	v_readlane_b32 s0, v248, 26
	v_subrev_u32_e32 v128, 32, v186
	v_readlane_b32 s1, v248, 27
	s_movk_i32 s4, 0x180
	s_nop 0
	v_lshl_add_u64 v[132:133], s[0:1], 0, v[128:129]
	v_mad_u64_u32 v[134:135], s[0:1], v132, s4, v[150:151]
	v_mad_u32_u24 v135, v133, s4, v135
	global_store_dwordx4 v[134:135], v[108:111], off
	global_store_dwordx4 v[134:135], v[104:107], off offset:128
	global_store_dwordx4 v[134:135], v[96:99], off offset:256
